# rowsum items: W1^T row loads issued with the gain loads (before the 16 b/g divisions), consumed via first-iteration path
# baseline (speedup 1.0000x reference)
.Lrs_item:
	s_mov_b64 s[10:11], s[0:1]
	s_load_dwordx4 s[24:27], s[10:11], 0xb8
	s_load_dwordx2 s[28:29], s[10:11], 0xd0
	s_mov_b32 s30, s74
	s_waitcnt vmcnt(7)
	v_mov_b32_e32 v0, v236
	s_add_i32 s4, s81, 0xfffffcfa
	s_lshl_b32 s4, s4, 3
	s_waitcnt vmcnt(0)
	v_and_b32_e32 v29, 63, v0
	v_ashrrev_i32_e32 v0, 6, v0
	v_add_u32_e32 v28, s4, v0
	v_cmp_gt_i32_e32 vcc, s73, v28
	s_and_saveexec_b64 s[34:35], vcc
	s_cbranch_execz .LBB0_966
	s_load_dwordx4 s[20:23], s[10:11], 0x98
	s_lshl_b32 s10, s30, 12
	s_ashr_i32 s11, s10, 31
	s_lshl_b64 s[10:11], s[10:11], 2
	s_waitcnt lgkmcnt(0)
	s_add_u32 s4, s28, s10
	s_addc_u32 s10, s29, s11
	s_add_u32 s36, s4, 0xef8e000
	s_addc_u32 s37, s10, 0
	s_add_u32 s38, s4, 0xef96000
	s_addc_u32 s39, s10, 0
	s_lshl_b32 s10, s30, 10
	s_ashr_i32 s11, s10, 31
	s_lshl_b64 s[10:11], s[10:11], 2
	s_add_u32 s12, s22, s10
	s_addc_u32 s13, s23, s11
	s_add_u32 s10, s20, s10
	v_lshlrev_b32_e32 v30, 6, v29
	s_addc_u32 s11, s21, s11
	global_load_dwordx4 v[0:3], v30, s[12:13] offset:48
	global_load_dwordx4 v[8:11], v30, s[12:13] offset:32
	global_load_dwordx4 v[16:19], v30, s[12:13] offset:16
	global_load_dwordx4 v[24:27], v30, s[12:13]
	global_load_dwordx4 v[4:7], v30, s[10:11] offset:48
	global_load_dwordx4 v[12:15], v30, s[10:11] offset:32
	global_load_dwordx4 v[20:23], v30, s[10:11] offset:16
	s_nop 0
	global_load_dwordx4 v[30:33], v30, s[10:11]
	s_ashr_i32 s31, s30, 31
	s_lshl_b64 s[16:17], s[30:31], 23
	s_add_u32 s22, s28, s16
	s_addc_u32 s23, s29, s17
	v_lshlrev_b32_e32 v174, 5, v29
	s_mov_b64 s[40:41], 0
	v_mov_b32_e32 v131, 0
	v_lshlrev_b32_e32 v130, 5, v29
	v_lshl_add_u64 v[130:131], s[22:23], 0, v[130:131]
	s_mov_b64 s[10:11], 0xa00000
	v_lshl_add_u64 v[130:131], v[130:131], 0, s[10:11]
	v_mov_b32_e32 v132, v28
	v_ashrrev_i32_e32 v133, 31, v28
	v_lshlrev_b64 v[132:133], 11, v[132:133]
	v_lshl_add_u64 v[132:133], v[130:131], 0, v[132:133]
	v_add_u32_e32 v134, s56, v28
	v_ashrrev_i32_e32 v135, 31, v134
	v_lshlrev_b64 v[134:135], 11, v[134:135]
	v_lshl_add_u64 v[134:135], v[130:131], 0, v[134:135]
	global_load_dwordx4 v[136:139], v[132:133], off offset:16
	global_load_dwordx4 v[140:143], v[132:133], off
	global_load_dwordx4 v[144:147], v[134:135], off offset:16
	global_load_dwordx4 v[148:151], v[134:135], off
	s_waitcnt vmcnt(4)
	v_div_scale_f32 v34, s[10:11], v30, v30, v24
	v_rcp_f32_e32 v35, v34
	s_nop 0
	v_fma_f32 v36, -v34, v35, 1.0
	v_fmac_f32_e32 v35, v36, v35
	v_div_scale_f32 v36, vcc, v24, v30, v24
	v_mul_f32_e32 v37, v36, v35
	v_fma_f32 v38, -v34, v37, v36
	v_fmac_f32_e32 v37, v38, v35
	v_fma_f32 v34, -v34, v37, v36
	v_div_fmas_f32 v34, v34, v35, v37
	v_div_fixup_f32 v24, v34, v30, v24
	v_div_scale_f32 v30, s[10:11], v31, v31, v25
	v_rcp_f32_e32 v34, v30
	s_nop 0
	v_fma_f32 v35, -v30, v34, 1.0
	v_fmac_f32_e32 v34, v35, v34
	v_div_scale_f32 v35, vcc, v25, v31, v25
	v_mul_f32_e32 v36, v35, v34
	v_fma_f32 v37, -v30, v36, v35
	v_fmac_f32_e32 v36, v37, v34
	v_fma_f32 v30, -v30, v36, v35
	v_div_fmas_f32 v30, v30, v34, v36
	v_div_fixup_f32 v25, v30, v31, v25
	v_div_scale_f32 v30, s[10:11], v32, v32, v26
	v_rcp_f32_e32 v31, v30
	s_nop 0
	v_fma_f32 v34, -v30, v31, 1.0
	v_fmac_f32_e32 v31, v34, v31
	v_div_scale_f32 v34, vcc, v26, v32, v26
	v_mul_f32_e32 v35, v34, v31
	v_fma_f32 v36, -v30, v35, v34
	v_fmac_f32_e32 v35, v36, v31
	v_fma_f32 v30, -v30, v35, v34
	v_div_fmas_f32 v30, v30, v31, v35
	v_div_fixup_f32 v26, v30, v32, v26
	v_div_scale_f32 v30, s[10:11], v33, v33, v27
	v_rcp_f32_e32 v31, v30
	s_nop 0
	v_fma_f32 v32, -v30, v31, 1.0
	v_fmac_f32_e32 v31, v32, v31
	v_div_scale_f32 v32, vcc, v27, v33, v27
	v_mul_f32_e32 v34, v32, v31
	v_fma_f32 v35, -v30, v34, v32
	v_fmac_f32_e32 v34, v35, v31
	v_fma_f32 v30, -v30, v34, v32
	v_div_fmas_f32 v30, v30, v31, v34
	v_div_fixup_f32 v27, v30, v33, v27
	v_div_scale_f32 v30, s[10:11], v20, v20, v16
	v_rcp_f32_e32 v31, v30
	s_nop 0
	v_fma_f32 v32, -v30, v31, 1.0
	v_fmac_f32_e32 v31, v32, v31
	v_div_scale_f32 v32, vcc, v16, v20, v16
	v_mul_f32_e32 v33, v32, v31
	v_fma_f32 v34, -v30, v33, v32
	v_fmac_f32_e32 v33, v34, v31
	v_fma_f32 v30, -v30, v33, v32
	v_div_fmas_f32 v30, v30, v31, v33
	v_div_fixup_f32 v16, v30, v20, v16
	v_div_scale_f32 v20, s[10:11], v21, v21, v17
	v_rcp_f32_e32 v30, v20
	s_nop 0
	v_fma_f32 v31, -v20, v30, 1.0
	v_fmac_f32_e32 v30, v31, v30
	v_div_scale_f32 v31, vcc, v17, v21, v17
	v_mul_f32_e32 v32, v31, v30
	v_fma_f32 v33, -v20, v32, v31
	v_fmac_f32_e32 v32, v33, v30
	v_fma_f32 v20, -v20, v32, v31
	v_div_fmas_f32 v20, v20, v30, v32
	v_div_fixup_f32 v17, v20, v21, v17
	v_div_scale_f32 v20, s[10:11], v22, v22, v18
	v_rcp_f32_e32 v21, v20
	s_nop 0
	v_fma_f32 v30, -v20, v21, 1.0
	v_fmac_f32_e32 v21, v30, v21
	v_div_scale_f32 v30, vcc, v18, v22, v18
	v_mul_f32_e32 v31, v30, v21
	v_fma_f32 v32, -v20, v31, v30
	v_fmac_f32_e32 v31, v32, v21
	v_fma_f32 v20, -v20, v31, v30
	v_div_fmas_f32 v20, v20, v21, v31
	v_div_fixup_f32 v18, v20, v22, v18
	v_div_scale_f32 v20, s[10:11], v23, v23, v19
	v_rcp_f32_e32 v21, v20
	s_nop 0
	v_fma_f32 v22, -v20, v21, 1.0
	v_fmac_f32_e32 v21, v22, v21
	v_div_scale_f32 v22, vcc, v19, v23, v19
	v_mul_f32_e32 v30, v22, v21
	v_fma_f32 v31, -v20, v30, v22
	v_fmac_f32_e32 v30, v31, v21
	v_fma_f32 v20, -v20, v30, v22
	v_div_fmas_f32 v20, v20, v21, v30
	v_div_fixup_f32 v19, v20, v23, v19
	v_div_scale_f32 v20, s[10:11], v12, v12, v8
	v_rcp_f32_e32 v21, v20
	s_nop 0
	v_fma_f32 v22, -v20, v21, 1.0
	v_fmac_f32_e32 v21, v22, v21
	v_div_scale_f32 v22, vcc, v8, v12, v8
	v_mul_f32_e32 v23, v22, v21
	v_fma_f32 v30, -v20, v23, v22
	v_fmac_f32_e32 v23, v30, v21
	v_fma_f32 v20, -v20, v23, v22
	v_div_fmas_f32 v20, v20, v21, v23
	v_div_fixup_f32 v20, v20, v12, v8
	v_div_scale_f32 v8, s[10:11], v13, v13, v9
	v_rcp_f32_e32 v12, v8
	s_nop 0
	v_fma_f32 v21, -v8, v12, 1.0
	v_fmac_f32_e32 v12, v21, v12
	v_div_scale_f32 v21, vcc, v9, v13, v9
	v_mul_f32_e32 v22, v21, v12
	v_fma_f32 v23, -v8, v22, v21
	v_fmac_f32_e32 v22, v23, v12
	v_fma_f32 v8, -v8, v22, v21
	v_div_fmas_f32 v8, v8, v12, v22
	v_div_fixup_f32 v21, v8, v13, v9
	v_div_scale_f32 v8, s[10:11], v14, v14, v10
	v_rcp_f32_e32 v9, v8
	s_nop 0
	v_fma_f32 v12, -v8, v9, 1.0
	v_fmac_f32_e32 v9, v12, v9
	v_div_scale_f32 v12, vcc, v10, v14, v10
	v_mul_f32_e32 v13, v12, v9
	v_fma_f32 v22, -v8, v13, v12
	v_fmac_f32_e32 v13, v22, v9
	v_fma_f32 v8, -v8, v13, v12
	v_div_fmas_f32 v8, v8, v9, v13
	v_div_fixup_f32 v22, v8, v14, v10
	v_div_scale_f32 v8, s[10:11], v15, v15, v11
	v_rcp_f32_e32 v9, v8
	v_mov_b32_e32 v14, v28
	v_fma_f32 v10, -v8, v9, 1.0
	v_fmac_f32_e32 v9, v10, v9
	v_div_scale_f32 v10, vcc, v11, v15, v11
	v_mul_f32_e32 v12, v10, v9
	v_fma_f32 v13, -v8, v12, v10
	v_fmac_f32_e32 v12, v13, v9
	v_fma_f32 v8, -v8, v12, v10
	v_div_fmas_f32 v8, v8, v9, v12
	v_div_fixup_f32 v23, v8, v15, v11
	v_div_scale_f32 v8, s[10:11], v4, v4, v0
	v_rcp_f32_e32 v9, v8
	s_nop 0
	v_fma_f32 v10, -v8, v9, 1.0
	v_fmac_f32_e32 v9, v10, v9
	v_div_scale_f32 v10, vcc, v0, v4, v0
	v_mul_f32_e32 v11, v10, v9
	v_fma_f32 v12, -v8, v11, v10
	v_fmac_f32_e32 v11, v12, v9
	v_fma_f32 v8, -v8, v11, v10
	v_div_fmas_f32 v8, v8, v9, v11
	v_div_fixup_f32 v30, v8, v4, v0
	v_div_scale_f32 v0, s[10:11], v5, v5, v1
	v_rcp_f32_e32 v4, v0
	s_nop 0
	v_fma_f32 v8, -v0, v4, 1.0
	v_fmac_f32_e32 v4, v8, v4
	v_div_scale_f32 v8, vcc, v1, v5, v1
	v_mul_f32_e32 v9, v8, v4
	v_fma_f32 v10, -v0, v9, v8
	v_fmac_f32_e32 v9, v10, v4
	v_fma_f32 v0, -v0, v9, v8
	v_div_fmas_f32 v0, v0, v4, v9
	v_div_fixup_f32 v31, v0, v5, v1
	v_div_scale_f32 v0, s[10:11], v6, v6, v2
	v_rcp_f32_e32 v1, v0
	s_nop 0
	v_fma_f32 v4, -v0, v1, 1.0
	v_fmac_f32_e32 v1, v4, v1
	v_div_scale_f32 v4, vcc, v2, v6, v2
	v_mul_f32_e32 v5, v4, v1
	v_fma_f32 v8, -v0, v5, v4
	v_fmac_f32_e32 v5, v8, v1
	v_fma_f32 v0, -v0, v5, v4
	v_div_fmas_f32 v0, v0, v1, v5
	v_div_fixup_f32 v32, v0, v6, v2
	v_div_scale_f32 v0, s[10:11], v7, v7, v3
	v_rcp_f32_e32 v1, v0
	s_mov_b64 s[10:11], 0xa00000
	v_fma_f32 v2, -v0, v1, 1.0
	v_fmac_f32_e32 v1, v2, v1
	v_div_scale_f32 v2, vcc, v3, v7, v3
	v_mul_f32_e32 v4, v2, v1
	v_fma_f32 v5, -v0, v4, v2
	v_fmac_f32_e32 v4, v5, v1
	v_fma_f32 v0, -v0, v4, v2
	v_div_fmas_f32 v0, v0, v1, v4
	v_div_fixup_f32 v33, v0, v7, v3
	v_lshl_add_u64 v[0:1], s[22:23], 0, v[174:175]
	v_lshl_add_u64 v[12:13], v[0:1], 0, s[10:11]
	v_and_b32_e32 v0, 64, v237
	v_add_u32_e32 v0, 64, v0
	v_xor_b32_e32 v1, 1, v237
	v_cmp_lt_i32_e32 vcc, v1, v0
	s_nop 1
	v_cndmask_b32_e32 v1, v237, v1, vcc
	v_lshlrev_b32_e32 v34, 2, v1
	v_xor_b32_e32 v1, 2, v237
	v_cmp_lt_i32_e32 vcc, v1, v0
	s_nop 1
	v_cndmask_b32_e32 v1, v237, v1, vcc
	v_lshlrev_b32_e32 v35, 2, v1
	v_xor_b32_e32 v1, 4, v237
	v_cmp_lt_i32_e32 vcc, v1, v0
	s_nop 1
	v_cndmask_b32_e32 v1, v237, v1, vcc
	v_lshlrev_b32_e32 v36, 2, v1
	v_xor_b32_e32 v1, 8, v237
	v_cmp_lt_i32_e32 vcc, v1, v0
	s_nop 1
	v_cndmask_b32_e32 v1, v237, v1, vcc
	v_lshlrev_b32_e32 v37, 2, v1
	v_xor_b32_e32 v1, 16, v237
	v_cmp_lt_i32_e32 vcc, v1, v0
	s_nop 1
	v_cndmask_b32_e32 v1, v237, v1, vcc
	v_lshlrev_b32_e32 v38, 2, v1
	v_xor_b32_e32 v1, 32, v237
	v_cmp_lt_i32_e32 vcc, v1, v0
	s_nop 1
	v_cndmask_b32_e32 v0, v237, v1, vcc
	v_lshlrev_b32_e32 v39, 2, v0
	v_cmp_eq_u32_e32 vcc, 0, v29
	s_branch .Lrs_first1

.LBB0_963:
	v_add_u32_e32 v40, s56, v14
	v_cmp_gt_i32_e64 s[22:23], s73, v40
	v_ashrrev_i32_e32 v15, 31, v14
	v_lshlrev_b64 v[0:1], 11, v[14:15]
	v_cndmask_b32_e64 v2, v14, v40, s[22:23]
	v_ashrrev_i32_e32 v3, 31, v2
	v_lshlrev_b64 v[2:3], 11, v[2:3]
	v_lshl_add_u64 v[0:1], v[12:13], 0, v[0:1]
	v_lshl_add_u64 v[4:5], v[12:13], 0, v[2:3]
	s_waitcnt lgkmcnt(1)
	global_load_dwordx4 v[8:11], v[0:1], off offset:16
	global_load_dwordx4 v[42:45], v[0:1], off
	s_nop 0
	global_load_dwordx4 v[0:3], v[4:5], off offset:16
	s_waitcnt lgkmcnt(0)
	global_load_dwordx4 v[4:7], v[4:5], off
	s_branch .Lrs_join1
.Lrs_first1:
	v_add_u32_e32 v40, s56, v14
	v_cmp_gt_i32_e64 s[22:23], s73, v40
	v_ashrrev_i32_e32 v15, 31, v14
	s_waitcnt vmcnt(0)
	v_mov_b32_e32 v8, v136
	v_mov_b32_e32 v9, v137
	v_mov_b32_e32 v10, v138
	v_mov_b32_e32 v11, v139
	v_mov_b32_e32 v42, v140
	v_mov_b32_e32 v43, v141
	v_mov_b32_e32 v44, v142
	v_mov_b32_e32 v45, v143
	v_mov_b32_e32 v0, v144
	v_mov_b32_e32 v1, v145
	v_mov_b32_e32 v2, v146
	v_mov_b32_e32 v3, v147
	v_mov_b32_e32 v4, v148
	v_mov_b32_e32 v5, v149
	v_mov_b32_e32 v6, v150
	v_mov_b32_e32 v7, v151
.Lrs_join1:
	s_waitcnt vmcnt(2)
	v_lshlrev_b32_e32 v41, 16, v42
	v_and_b32_e32 v42, 0xffff0000, v42
	v_add_f32_e32 v46, v41, v42
	v_mul_f32_e32 v42, v25, v42
	v_fmac_f32_e32 v42, v24, v41
	v_add_f32_e32 v41, 0, v42
	v_lshlrev_b32_e32 v42, 16, v43
	v_and_b32_e32 v43, 0xffff0000, v43
	v_add_f32_e32 v47, v42, v43
	v_mul_f32_e32 v43, v27, v43
	v_fmac_f32_e32 v43, v26, v42
	v_add_f32_e32 v41, v43, v41
	v_lshlrev_b32_e32 v42, 16, v44
	v_and_b32_e32 v43, 0xffff0000, v44
	v_add_f32_e32 v44, v42, v43
	v_mul_f32_e32 v43, v17, v43
	v_fmac_f32_e32 v43, v16, v42
	v_add_f32_e32 v41, v43, v41
	v_lshlrev_b32_e32 v42, 16, v45
	v_and_b32_e32 v43, 0xffff0000, v45
	v_add_f32_e32 v45, v42, v43
	v_mul_f32_e32 v43, v19, v43
	v_fmac_f32_e32 v43, v18, v42
	v_lshlrev_b32_e32 v42, 16, v8
	v_and_b32_e32 v8, 0xffff0000, v8
	v_add_f32_e32 v41, v43, v41
	v_add_f32_e32 v43, v42, v8
	v_mul_f32_e32 v8, v21, v8
	v_fmac_f32_e32 v8, v20, v42
	v_add_f32_e32 v8, v8, v41
	v_lshlrev_b32_e32 v41, 16, v9
	v_and_b32_e32 v9, 0xffff0000, v9
	v_add_f32_e32 v46, 0, v46
	v_add_f32_e32 v42, v41, v9
	v_mul_f32_e32 v9, v23, v9
	v_add_f32_e32 v46, v47, v46
	v_fmac_f32_e32 v9, v22, v41
	v_add_f32_e32 v44, v44, v46
	v_add_f32_e32 v8, v9, v8
	v_lshlrev_b32_e32 v9, 16, v10
	v_and_b32_e32 v10, 0xffff0000, v10
	v_add_f32_e32 v44, v45, v44
	v_add_f32_e32 v41, v9, v10
	v_mul_f32_e32 v10, v31, v10
	v_add_f32_e32 v43, v43, v44
	v_fmac_f32_e32 v10, v30, v9
	v_add_f32_e32 v42, v42, v43
	v_add_f32_e32 v8, v10, v8
	v_lshlrev_b32_e32 v9, 16, v11
	v_and_b32_e32 v10, 0xffff0000, v11
	v_add_f32_e32 v41, v41, v42
	v_add_f32_e32 v11, v9, v10
	v_add_f32_e32 v11, v11, v41
	s_waitcnt vmcnt(0)
	v_lshlrev_b32_e32 v41, 16, v4
	v_and_b32_e32 v4, 0xffff0000, v4
	v_add_f32_e32 v42, v41, v4
	v_mul_f32_e32 v4, v25, v4
	v_fmac_f32_e32 v4, v24, v41
	v_lshlrev_b32_e32 v41, 16, v5
	v_and_b32_e32 v5, 0xffff0000, v5
	v_add_f32_e32 v43, v41, v5
	v_mul_f32_e32 v5, v27, v5
	v_add_f32_e32 v4, 0, v4
	v_fmac_f32_e32 v5, v26, v41
	v_add_f32_e32 v4, v5, v4
	v_lshlrev_b32_e32 v5, 16, v6
	v_and_b32_e32 v6, 0xffff0000, v6
	v_add_f32_e32 v41, v5, v6
	v_mul_f32_e32 v6, v17, v6
	v_fmac_f32_e32 v6, v16, v5
	v_add_f32_e32 v4, v6, v4
	v_lshlrev_b32_e32 v5, 16, v7
	v_and_b32_e32 v6, 0xffff0000, v7
	v_add_f32_e32 v7, v5, v6
	v_mul_f32_e32 v6, v19, v6
	v_fmac_f32_e32 v6, v18, v5
	v_lshlrev_b32_e32 v5, 16, v0
	v_and_b32_e32 v0, 0xffff0000, v0
	v_add_f32_e32 v4, v6, v4
	v_add_f32_e32 v6, v5, v0
	v_mul_f32_e32 v0, v21, v0
	v_fmac_f32_e32 v0, v20, v5
	v_add_f32_e32 v0, v0, v4
	v_lshlrev_b32_e32 v4, 16, v1
	v_and_b32_e32 v1, 0xffff0000, v1
	v_add_f32_e32 v42, 0, v42
	v_add_f32_e32 v5, v4, v1
	v_mul_f32_e32 v1, v23, v1
	v_add_f32_e32 v42, v43, v42
	v_fmac_f32_e32 v1, v22, v4
	v_add_f32_e32 v41, v41, v42
	v_add_f32_e32 v0, v1, v0
	v_lshlrev_b32_e32 v1, 16, v2
	v_and_b32_e32 v2, 0xffff0000, v2
	v_add_f32_e32 v7, v7, v41
	v_add_f32_e32 v4, v1, v2
	v_mul_f32_e32 v2, v31, v2
	v_add_f32_e32 v6, v6, v7
	v_fmac_f32_e32 v2, v30, v1
	v_add_f32_e32 v5, v5, v6
	v_add_f32_e32 v0, v2, v0
	v_lshlrev_b32_e32 v1, 16, v3
	v_and_b32_e32 v2, 0xffff0000, v3
	v_mul_f32_e32 v10, v33, v10
	v_add_f32_e32 v4, v4, v5
	v_add_f32_e32 v3, v1, v2
	v_mul_f32_e32 v2, v33, v2
	v_fmac_f32_e32 v10, v32, v9
	v_add_f32_e32 v3, v3, v4
	v_fmac_f32_e32 v2, v32, v1
	v_add_f32_e32 v8, v10, v8
	ds_bpermute_b32 v9, v34, v11
	v_add_f32_e32 v0, v2, v0
	ds_bpermute_b32 v1, v34, v3
	ds_bpermute_b32 v10, v34, v8
	ds_bpermute_b32 v2, v34, v0
	s_waitcnt lgkmcnt(3)
	v_add_f32_e32 v9, v11, v9
	s_waitcnt lgkmcnt(2)
	v_add_f32_e32 v1, v3, v1
	s_waitcnt lgkmcnt(1)
	v_add_f32_e32 v8, v8, v10
	ds_bpermute_b32 v10, v35, v9
	s_waitcnt lgkmcnt(1)
	v_add_f32_e32 v0, v0, v2
	ds_bpermute_b32 v2, v35, v1
	s_waitcnt lgkmcnt(1)
	v_add_f32_e32 v9, v9, v10
	ds_bpermute_b32 v10, v35, v8
	s_waitcnt lgkmcnt(1)
	v_add_f32_e32 v1, v1, v2
	ds_bpermute_b32 v2, v35, v0
	s_waitcnt lgkmcnt(1)
	v_add_f32_e32 v8, v8, v10
	ds_bpermute_b32 v10, v36, v9
	s_waitcnt lgkmcnt(1)
	v_add_f32_e32 v0, v0, v2
	ds_bpermute_b32 v2, v36, v1
	s_waitcnt lgkmcnt(1)
	v_add_f32_e32 v9, v9, v10
	ds_bpermute_b32 v10, v36, v8
	s_waitcnt lgkmcnt(1)
	v_add_f32_e32 v1, v1, v2
	ds_bpermute_b32 v2, v36, v0
	s_waitcnt lgkmcnt(1)
	v_add_f32_e32 v8, v8, v10
	ds_bpermute_b32 v10, v37, v9
	s_waitcnt lgkmcnt(1)
	v_add_f32_e32 v0, v0, v2
	ds_bpermute_b32 v2, v37, v1
	s_waitcnt lgkmcnt(1)
	v_add_f32_e32 v9, v9, v10
	ds_bpermute_b32 v10, v37, v8
	s_waitcnt lgkmcnt(1)
	v_add_f32_e32 v1, v1, v2
	ds_bpermute_b32 v2, v37, v0
	s_waitcnt lgkmcnt(1)
	v_add_f32_e32 v10, v8, v10
	ds_bpermute_b32 v8, v38, v9
	s_waitcnt lgkmcnt(1)
	v_add_f32_e32 v0, v0, v2
	ds_bpermute_b32 v2, v38, v1
	s_waitcnt lgkmcnt(1)
	v_add_f32_e32 v8, v9, v8
	ds_bpermute_b32 v9, v38, v10
	s_waitcnt lgkmcnt(1)
	v_add_f32_e32 v4, v1, v2
	ds_bpermute_b32 v1, v38, v0
	ds_bpermute_b32 v6, v39, v4
	s_waitcnt lgkmcnt(2)
	v_add_f32_e32 v9, v10, v9
	ds_bpermute_b32 v10, v39, v8
	s_waitcnt lgkmcnt(2)
	v_add_f32_e32 v5, v0, v1
	ds_bpermute_b32 v11, v39, v9
	ds_bpermute_b32 v7, v39, v5
	s_and_saveexec_b64 s[10:11], vcc
	s_cbranch_execz .LBB0_962
	v_lshlrev_b64 v[2:3], 2, v[14:15]
	s_waitcnt lgkmcnt(1)
	v_add_f32_e32 v9, v9, v11
	v_add_f32_e32 v8, v8, v10
	v_lshl_add_u64 v[0:1], s[36:37], 0, v[2:3]
	v_lshl_add_u64 v[2:3], s[38:39], 0, v[2:3]
	global_store_dword v[0:1], v8, off
	global_store_dword v[2:3], v9, off
	s_and_b64 exec, exec, s[22:23]
	s_cbranch_execz .LBB0_962
	s_lshl_b64 s[12:13], s[56:57], 2
	v_add_f32_e32 v4, v4, v6
	v_lshl_add_u64 v[0:1], v[0:1], 0, s[12:13]
	s_waitcnt lgkmcnt(0)
	v_add_f32_e32 v5, v5, v7
	v_lshl_add_u64 v[2:3], v[2:3], 0, s[12:13]
	global_store_dword v[0:1], v4, off
	global_store_dword v[2:3], v5, off
	s_branch .LBB0_962
